# LDS-DMA in the P1 and P5 K-loops uses SGPR base + 32-bit lane offset (no per-load 64-bit VALU address add)
# speedup vs baseline: 1.0140x; 1.0129x over previous
; #define PG8_STAGE(bufoff, gbase, voff) do { _Pragma("unroll") for (int _i = 0; _i < 2; ++_i) \
;         __builtin_amdgcn_global_load_lds((const unsigned*)((const char*)(gbase) + (voff)[_i]), (PG8_LAS unsigned*)(lds + (bufoff) + ldsw + _i * 8192), 16, 0, 0); } while (0)
; #define PG8_LDA(dst, b, h) do { _Pragma("unroll") for (int m = 0; m < 4; ++m) _Pragma("unroll") for (int k = 0; k < 2; ++k) dst[m][k] = *(const PG8_LAS bf16x8*)(lds + PG8_SA(b, h) + aoff + m * 2048 + k * 1024); } while (0)
; #define PG8_LDB(dst, b, h) do { _Pragma("unroll") for (int n = 0; n < 2; ++n) _Pragma("unroll") for (int k = 0; k < 2; ++k) dst[n][k] = *(const PG8_LAS bf16x8*)(lds + PG8_SB(b, h) + boff + n * 2048 + k * 1024); } while (0)
; #define PG8_MMA(ai, bj, At, Bt) do { __builtin_amdgcn_s_setprio(1); _Pragma("unroll") for (int m = 0; m < 4; ++m) _Pragma("unroll") for (int n = 0; n < 2; ++n) _Pragma("unroll") for (int k = 0; k < 2; ++k) \
;         acc[ai][bj][m][n] = __builtin_amdgcn_mfma_f32_16x16x32_bf16(Bt[n][k], At[m][k], acc[ai][bj][m][n], 0, 0, 0); __builtin_amdgcn_s_setprio(0); } while (0)
; #define PG8_WAIT_V(n) asm volatile("s_waitcnt vmcnt(" #n ")" ::: "memory")
; #define PG8_WAIT_L(n) asm volatile("s_waitcnt lgkmcnt(" #n ")" ::: "memory")
; #define PG8_BAR __builtin_amdgcn_s_barrier()
; #define PG8_SCHED __builtin_amdgcn_sched_barrier(0)
; template <class Epi, class Sched, bool ALIGN_EPI = false, bool SP2 = false, bool SPLITK = false>
; __device__ __forceinline__ void gemm_phase(PG8_LAS unsigned char* lds, const Gemm g, const Sched& S, const Epi& E) {
;     ...
;             PG8_LDB(B0, 0, 0); PG8_LDB(B1, 0, 1); PG8_SCHED; PG8_LDA(At, 0, 0); PG8_STAGE(PG8_SA(1, 1), a1 + hstep, voffA);
;             PG8_WAIT_V(8); PG8_WAIT_L(0); PG8_BAR; PG8_MMA(0, 0, At, B0); PG8_MMA(0, 1, At, B1); PG8_BAR; PG8_SCHED;
;             PG8_LDA(At, 0, 1); PG8_STAGE(PG8_SB(0, 0), b2, voffB); PG8_STAGE(PG8_SB(0, 1), b2 + hstep, voffB); PG8_STAGE(PG8_SA(0, 0), a2, voffA);
;             PG8_WAIT_V(8); PG8_WAIT_L(0); PG8_BAR; PG8_MMA(1, 0, At, B0); PG8_MMA(1, 1, At, B1); PG8_BAR; PG8_SCHED;
.LBB0_165:
	s_add_u32 s35, s54, 0xfffc0080
	s_addc_u32 s43, s55, -1
	s_add_i32 s45, 0, 0x10000
	s_cmp_eq_u32 s25, 12
	s_cselect_b32 s49, s4, s43
	s_cselect_b32 s48, s12, s35
	s_cselect_b32 s47, s21, s24
	s_cselect_b32 s46, s22, s23
	s_add_i32 s35, 0, 0x14000
	v_add_u32_e32 v142, s45, v198
	v_add_u32_e32 v158, s35, v198
	ds_read_b128 v[130:133], v142
	ds_read_b128 v[134:137], v142 offset:1024
	ds_read_b128 v[138:141], v142 offset:2048
	ds_read_b128 v[142:145], v142 offset:3072
	ds_read_b128 v[146:149], v158
	ds_read_b128 v[150:153], v158 offset:1024
	ds_read_b128 v[154:157], v158 offset:2048
	ds_read_b128 v[158:161], v158 offset:3072
	s_add_i32 m0, s51, 0xc000
	ds_read_b128 v[162:165], v199
	s_waitcnt lgkmcnt(0)
	ds_read_b128 v[178:181], v199 offset:1024
	ds_read_b128 v[182:185], v199 offset:2048
	ds_read_b128 v[186:189], v199 offset:3072
	ds_read_b128 v[190:193], v199 offset:4096
	ds_read_b128 v[200:203], v199 offset:5120
	ds_read_b128 v[204:207], v199 offset:6144
	ds_read_b128 v[208:211], v199 offset:7168
	global_load_lds_dwordx4 v174, s[54:55]
	s_add_i32 m0, s51, 0xe000
	s_nop 0
	global_load_lds_dwordx4 v176, s[54:55]
	s_waitcnt vmcnt(8)
	s_waitcnt lgkmcnt(0)
	s_barrier
	s_setprio 1
	s_waitcnt lgkmcnt(0)
	v_mfma_f32_16x16x32_bf16 v[126:129], v[130:133], v[162:165], v[126:129]
	v_mfma_f32_16x16x32_bf16 v[122:125], v[138:141], v[162:165], v[122:125]
	v_mfma_f32_16x16x32_bf16 v[114:117], v[130:133], v[182:185], v[114:117]
	v_mfma_f32_16x16x32_bf16 v[106:109], v[138:141], v[182:185], v[106:109]
	v_mfma_f32_16x16x32_bf16 v[98:101], v[130:133], v[190:193], v[98:101]
	v_mfma_f32_16x16x32_bf16 v[90:93], v[138:141], v[190:193], v[90:93]
	v_mfma_f32_16x16x32_bf16 v[82:85], v[130:133], v[204:207], v[82:85]
	v_mfma_f32_16x16x32_bf16 v[74:77], v[138:141], v[204:207], v[74:77]
	v_mfma_f32_16x16x32_bf16 v[126:129], v[134:137], v[178:181], v[126:129]
	v_mfma_f32_16x16x32_bf16 v[122:125], v[142:145], v[178:181], v[122:125]
	v_mfma_f32_16x16x32_bf16 v[114:117], v[134:137], v[186:189], v[114:117]
	v_mfma_f32_16x16x32_bf16 v[106:109], v[142:145], v[186:189], v[106:109]
	v_mfma_f32_16x16x32_bf16 v[98:101], v[134:137], v[200:203], v[98:101]
	v_mfma_f32_16x16x32_bf16 v[90:93], v[142:145], v[200:203], v[90:93]
	v_mfma_f32_16x16x32_bf16 v[82:85], v[134:137], v[208:211], v[82:85]
	v_mfma_f32_16x16x32_bf16 v[74:77], v[142:145], v[208:211], v[74:77]
	s_setprio 0
	s_setprio 1
	v_mfma_f32_16x16x32_bf16 v[118:121], v[146:149], v[162:165], v[118:121]
	v_mfma_f32_16x16x32_bf16 v[110:113], v[154:157], v[162:165], v[110:113]
	v_mfma_f32_16x16x32_bf16 v[102:105], v[146:149], v[182:185], v[102:105]
	v_mfma_f32_16x16x32_bf16 v[94:97], v[154:157], v[182:185], v[94:97]
	v_mfma_f32_16x16x32_bf16 v[86:89], v[146:149], v[190:193], v[86:89]
	v_mfma_f32_16x16x32_bf16 v[78:81], v[154:157], v[190:193], v[78:81]
	v_mfma_f32_16x16x32_bf16 v[70:73], v[146:149], v[204:207], v[70:73]
	v_mfma_f32_16x16x32_bf16 v[66:69], v[154:157], v[204:207], v[66:69]
	v_mfma_f32_16x16x32_bf16 v[118:121], v[150:153], v[178:181], v[118:121]
	v_mfma_f32_16x16x32_bf16 v[110:113], v[158:161], v[178:181], v[110:113]
	v_mfma_f32_16x16x32_bf16 v[102:105], v[150:153], v[186:189], v[102:105]
	v_mfma_f32_16x16x32_bf16 v[94:97], v[158:161], v[186:189], v[94:97]
	v_mfma_f32_16x16x32_bf16 v[86:89], v[150:153], v[200:203], v[86:89]
	v_mfma_f32_16x16x32_bf16 v[78:81], v[158:161], v[200:203], v[78:81]
	v_mfma_f32_16x16x32_bf16 v[70:73], v[150:153], v[208:211], v[70:73]
	v_mfma_f32_16x16x32_bf16 v[66:69], v[158:161], v[208:211], v[66:69]
	s_setprio 0
	s_barrier
	s_add_i32 s43, s45, s33
	s_mov_b32 m0, s43
	ds_read_b128 v[162:165], v199 offset:16384
	ds_read_b128 v[178:181], v199 offset:17408
	ds_read_b128 v[182:185], v199 offset:18432
	ds_read_b128 v[186:189], v199 offset:19456
	ds_read_b128 v[190:193], v199 offset:20480
	ds_read_b128 v[200:203], v199 offset:21504
	ds_read_b128 v[204:207], v199 offset:22528
	ds_read_b128 v[208:211], v199 offset:23552
	global_load_lds_dwordx4 v0, s[46:47]
	s_add_i32 m0, s43, 0x2000
	s_add_u32 s76, s46, 0x40000
	s_addc_u32 s77, s47, 0
	s_add_i32 s35, s35, s33
	global_load_lds_dwordx4 v172, s[46:47]
	s_mov_b32 m0, s35
	s_nop 0
	global_load_lds_dwordx4 v0, s[76:77]
	s_add_i32 m0, s35, 0x2000
	s_nop 0
	global_load_lds_dwordx4 v172, s[76:77]
	s_mov_b32 m0, s51
	s_nop 0
	global_load_lds_dwordx4 v168, s[48:49]
	s_mov_b32 m0, s53
	s_nop 0
	global_load_lds_dwordx4 v170, s[48:49]
	s_waitcnt vmcnt(8)
	s_waitcnt lgkmcnt(0)
	s_barrier
	s_setprio 1
	s_waitcnt lgkmcnt(0)
	v_mfma_f32_16x16x32_bf16 v[62:65], v[130:133], v[162:165], v[62:65]
	v_mfma_f32_16x16x32_bf16 v[58:61], v[138:141], v[162:165], v[58:61]
	v_mfma_f32_16x16x32_bf16 v[50:53], v[130:133], v[182:185], v[50:53]
	v_mfma_f32_16x16x32_bf16 v[42:45], v[138:141], v[182:185], v[42:45]
	v_mfma_f32_16x16x32_bf16 v[34:37], v[130:133], v[190:193], v[34:37]
	v_mfma_f32_16x16x32_bf16 v[26:29], v[138:141], v[190:193], v[26:29]
	v_mfma_f32_16x16x32_bf16 v[18:21], v[130:133], v[204:207], v[18:21]
	v_mfma_f32_16x16x32_bf16 v[10:13], v[138:141], v[204:207], v[10:13]
	v_mfma_f32_16x16x32_bf16 v[62:65], v[134:137], v[178:181], v[62:65]
	v_mfma_f32_16x16x32_bf16 v[58:61], v[142:145], v[178:181], v[58:61]
	v_mfma_f32_16x16x32_bf16 v[50:53], v[134:137], v[186:189], v[50:53]
	v_mfma_f32_16x16x32_bf16 v[42:45], v[142:145], v[186:189], v[42:45]
	v_mfma_f32_16x16x32_bf16 v[34:37], v[134:137], v[200:203], v[34:37]
	v_mfma_f32_16x16x32_bf16 v[26:29], v[142:145], v[200:203], v[26:29]
	v_mfma_f32_16x16x32_bf16 v[18:21], v[134:137], v[208:211], v[18:21]
	v_mfma_f32_16x16x32_bf16 v[10:13], v[142:145], v[208:211], v[10:13]
	s_setprio 0
	s_setprio 1
	v_mfma_f32_16x16x32_bf16 v[54:57], v[146:149], v[162:165], v[54:57]
	v_mfma_f32_16x16x32_bf16 v[46:49], v[154:157], v[162:165], v[46:49]
	v_mfma_f32_16x16x32_bf16 v[38:41], v[146:149], v[182:185], v[38:41]
	v_mfma_f32_16x16x32_bf16 v[30:33], v[154:157], v[182:185], v[30:33]
	v_mfma_f32_16x16x32_bf16 v[22:25], v[146:149], v[190:193], v[22:25]
	v_mfma_f32_16x16x32_bf16 v[14:17], v[154:157], v[190:193], v[14:17]
	v_mfma_f32_16x16x32_bf16 v[6:9], v[146:149], v[204:207], v[6:9]
	v_mfma_f32_16x16x32_bf16 v[2:5], v[154:157], v[204:207], v[2:5]
	v_mfma_f32_16x16x32_bf16 v[54:57], v[150:153], v[178:181], v[54:57]
	v_mfma_f32_16x16x32_bf16 v[46:49], v[158:161], v[178:181], v[46:49]
	v_mfma_f32_16x16x32_bf16 v[38:41], v[150:153], v[186:189], v[38:41]
	v_mfma_f32_16x16x32_bf16 v[30:33], v[158:161], v[186:189], v[30:33]
	v_mfma_f32_16x16x32_bf16 v[22:25], v[150:153], v[200:203], v[22:25]
	v_mfma_f32_16x16x32_bf16 v[14:17], v[158:161], v[200:203], v[14:17]
	v_mfma_f32_16x16x32_bf16 v[6:9], v[150:153], v[208:211], v[6:9]
	v_mfma_f32_16x16x32_bf16 v[2:5], v[158:161], v[208:211], v[2:5]
	s_setprio 0
	s_barrier
; #define PG8_STAGE(bufoff, gbase, voff) do { _Pragma("unroll") for (int _i = 0; _i < 2; ++_i) \
;         __builtin_amdgcn_global_load_lds((const unsigned*)((const char*)(gbase) + (voff)[_i]), (PG8_LAS unsigned*)(lds + (bufoff) + ldsw + _i * 8192), 16, 0, 0); } while (0)
; #define PG8_LDA(dst, b, h) do { _Pragma("unroll") for (int m = 0; m < 4; ++m) _Pragma("unroll") for (int k = 0; k < 2; ++k) dst[m][k] = *(const PG8_LAS bf16x8*)(lds + PG8_SA(b, h) + aoff + m * 2048 + k * 1024); } while (0)
; #define PG8_LDB(dst, b, h) do { _Pragma("unroll") for (int n = 0; n < 2; ++n) _Pragma("unroll") for (int k = 0; k < 2; ++k) dst[n][k] = *(const PG8_LAS bf16x8*)(lds + PG8_SB(b, h) + boff + n * 2048 + k * 1024); } while (0)
; #define PG8_MMA(ai, bj, At, Bt) do { __builtin_amdgcn_s_setprio(1); _Pragma("unroll") for (int m = 0; m < 4; ++m) _Pragma("unroll") for (int n = 0; n < 2; ++n) _Pragma("unroll") for (int k = 0; k < 2; ++k) \
;         acc[ai][bj][m][n] = __builtin_amdgcn_mfma_f32_16x16x32_bf16(Bt[n][k], At[m][k], acc[ai][bj][m][n], 0, 0, 0); __builtin_amdgcn_s_setprio(0); } while (0)
; #define PG8_WAIT_V(n) asm volatile("s_waitcnt vmcnt(" #n ")" ::: "memory")
; #define PG8_WAIT_L(n) asm volatile("s_waitcnt lgkmcnt(" #n ")" ::: "memory")
; template <class Epi, class Sched, bool ALIGN_EPI = false, bool SP2 = false, bool SPLITK = false>
; __device__ __forceinline__ void gemm_phase(PG8_LAS unsigned char* lds, const Gemm g, const Sched& S, const Epi& E) {
;     ...
;         for (int t = 0; t < nt; t += 2) {
;             const bool last = (t == nt - 2);
;             if constexpr (SPLITK) { if (t == nt1) E.mid(acc, cur, wr, wc, fr, fq); }
;             const char* a1 = PG8_TA(t + 1);
;             const char* a2 = last ? nA : PG8_TA(t + 2); const char* b2 = last ? nB : PG8_TB(t + 2);
;             const char* a3 = a2 + kstep; const char* b3 = b2 + kstep;
;     ...
;             PG8_LDB(B0, 1, 0); PG8_LDB(B1, 1, 1); PG8_SCHED; PG8_LDA(At, 1, 0); PG8_STAGE(PG8_SA(0, 1), a2 + hstep, voffA);
;             PG8_WAIT_V(8); PG8_WAIT_L(0); PG8_BAR; PG8_MMA(0, 0, At, B0); PG8_MMA(0, 1, At, B1); PG8_BAR; PG8_SCHED;
;             PG8_LDA(At, 1, 1); PG8_STAGE(PG8_SB(1, 0), b3, voffB); PG8_STAGE(PG8_SB(1, 1), b3 + hstep, voffB); PG8_STAGE(PG8_SA(1, 0), a3, voffA);
;             PG8_WAIT_V(8); PG8_WAIT_L(0); PG8_BAR; PG8_MMA(1, 0, At, B0); PG8_MMA(1, 1, At, B1); PG8_BAR; PG8_SCHED;
	s_add_i32 s35, 0, 0x18000
	s_add_i32 s43, 0, 0x1c000
	v_add_u32_e32 v142, s35, v198
	v_add_u32_e32 v158, s43, v198
	ds_read_b128 v[130:133], v142
	ds_read_b128 v[134:137], v142 offset:1024
	ds_read_b128 v[138:141], v142 offset:2048
	ds_read_b128 v[142:145], v142 offset:3072
	ds_read_b128 v[146:149], v158
	ds_read_b128 v[150:153], v158 offset:1024
	ds_read_b128 v[154:157], v158 offset:2048
	ds_read_b128 v[158:161], v158 offset:3072
	s_add_u32 s48, s48, 0x40000
	s_addc_u32 s49, s49, 0
	s_mov_b32 m0, s56
	ds_read_b128 v[162:165], v199 offset:32768
	ds_read_b128 v[178:181], v199 offset:33792
	ds_read_b128 v[182:185], v199 offset:34816
	ds_read_b128 v[186:189], v199 offset:35840
	ds_read_b128 v[190:193], v199 offset:36864
	ds_read_b128 v[200:203], v199 offset:37888
	ds_read_b128 v[204:207], v199 offset:38912
	ds_read_b128 v[208:211], v199 offset:39936
	global_load_lds_dwordx4 v168, s[48:49]
	s_mov_b32 m0, s57
	s_nop 0
	global_load_lds_dwordx4 v170, s[48:49]
	s_waitcnt vmcnt(8)
	s_waitcnt lgkmcnt(0)
	s_barrier
	s_setprio 1
	s_waitcnt lgkmcnt(0)
	v_mfma_f32_16x16x32_bf16 v[126:129], v[130:133], v[162:165], v[126:129]
	v_mfma_f32_16x16x32_bf16 v[122:125], v[138:141], v[162:165], v[122:125]
	v_mfma_f32_16x16x32_bf16 v[114:117], v[130:133], v[182:185], v[114:117]
	v_mfma_f32_16x16x32_bf16 v[106:109], v[138:141], v[182:185], v[106:109]
	v_mfma_f32_16x16x32_bf16 v[98:101], v[130:133], v[190:193], v[98:101]
	v_mfma_f32_16x16x32_bf16 v[90:93], v[138:141], v[190:193], v[90:93]
	v_mfma_f32_16x16x32_bf16 v[82:85], v[130:133], v[204:207], v[82:85]
	v_mfma_f32_16x16x32_bf16 v[74:77], v[138:141], v[204:207], v[74:77]
	v_mfma_f32_16x16x32_bf16 v[126:129], v[134:137], v[178:181], v[126:129]
	v_mfma_f32_16x16x32_bf16 v[122:125], v[142:145], v[178:181], v[122:125]
	v_mfma_f32_16x16x32_bf16 v[114:117], v[134:137], v[186:189], v[114:117]
	v_mfma_f32_16x16x32_bf16 v[106:109], v[142:145], v[186:189], v[106:109]
	v_mfma_f32_16x16x32_bf16 v[98:101], v[134:137], v[200:203], v[98:101]
	v_mfma_f32_16x16x32_bf16 v[90:93], v[142:145], v[200:203], v[90:93]
	v_mfma_f32_16x16x32_bf16 v[82:85], v[134:137], v[208:211], v[82:85]
	v_mfma_f32_16x16x32_bf16 v[74:77], v[142:145], v[208:211], v[74:77]
	s_setprio 0
	s_setprio 1
	v_mfma_f32_16x16x32_bf16 v[118:121], v[146:149], v[162:165], v[118:121]
	v_mfma_f32_16x16x32_bf16 v[110:113], v[154:157], v[162:165], v[110:113]
	v_mfma_f32_16x16x32_bf16 v[102:105], v[146:149], v[182:185], v[102:105]
	v_mfma_f32_16x16x32_bf16 v[94:97], v[154:157], v[182:185], v[94:97]
	v_mfma_f32_16x16x32_bf16 v[86:89], v[146:149], v[190:193], v[86:89]
	v_mfma_f32_16x16x32_bf16 v[78:81], v[154:157], v[190:193], v[78:81]
	v_mfma_f32_16x16x32_bf16 v[70:73], v[146:149], v[204:207], v[70:73]
	v_mfma_f32_16x16x32_bf16 v[66:69], v[154:157], v[204:207], v[66:69]
	v_mfma_f32_16x16x32_bf16 v[118:121], v[150:153], v[178:181], v[118:121]
	v_mfma_f32_16x16x32_bf16 v[110:113], v[158:161], v[178:181], v[110:113]
	v_mfma_f32_16x16x32_bf16 v[102:105], v[150:153], v[186:189], v[102:105]
	v_mfma_f32_16x16x32_bf16 v[94:97], v[158:161], v[186:189], v[94:97]
	v_mfma_f32_16x16x32_bf16 v[86:89], v[150:153], v[200:203], v[86:89]
	v_mfma_f32_16x16x32_bf16 v[78:81], v[158:161], v[200:203], v[78:81]
	v_mfma_f32_16x16x32_bf16 v[70:73], v[150:153], v[208:211], v[70:73]
	v_mfma_f32_16x16x32_bf16 v[66:69], v[158:161], v[208:211], v[66:69]
	s_setprio 0
	s_barrier
	s_add_i32 s35, s35, s33
	s_add_u32 s46, s46, 0x80
	s_addc_u32 s47, s47, 0
	s_mov_b32 m0, s35
	ds_read_b128 v[162:165], v199 offset:49152
	ds_read_b128 v[178:181], v199 offset:50176
	ds_read_b128 v[182:185], v199 offset:51200
	ds_read_b128 v[186:189], v199 offset:52224
	ds_read_b128 v[190:193], v199 offset:53248
	ds_read_b128 v[200:203], v199 offset:54272
	ds_read_b128 v[204:207], v199 offset:55296
	ds_read_b128 v[208:211], v199 offset:56320
	global_load_lds_dwordx4 v0, s[46:47]
	s_add_i32 m0, s35, 0x2000
	s_add_i32 s35, s43, s33
	global_load_lds_dwordx4 v172, s[46:47]
	s_add_u32 s46, s46, 0x40000
	s_addc_u32 s47, s47, 0
	s_mov_b32 m0, s35
	s_nop 0
	global_load_lds_dwordx4 v0, s[46:47]
	s_add_i32 m0, s35, 0x2000
	s_nop 0
	global_load_lds_dwordx4 v172, s[46:47]
	s_sub_u32 s76, s48, 0x3ff80
	s_subb_u32 s77, s49, 0
	s_mov_b32 m0, s58
	s_nop 0
	global_load_lds_dwordx4 v168, s[76:77]
	s_mov_b32 m0, s59
	s_nop 0
	global_load_lds_dwordx4 v170, s[76:77]
	s_waitcnt vmcnt(8)
	s_waitcnt lgkmcnt(0)
	s_barrier
	s_setprio 1
	s_waitcnt lgkmcnt(0)
	v_mfma_f32_16x16x32_bf16 v[62:65], v[130:133], v[162:165], v[62:65]
	v_mfma_f32_16x16x32_bf16 v[58:61], v[138:141], v[162:165], v[58:61]
	v_mfma_f32_16x16x32_bf16 v[50:53], v[130:133], v[182:185], v[50:53]
	v_mfma_f32_16x16x32_bf16 v[42:45], v[138:141], v[182:185], v[42:45]
	v_mfma_f32_16x16x32_bf16 v[34:37], v[130:133], v[190:193], v[34:37]
	v_mfma_f32_16x16x32_bf16 v[26:29], v[138:141], v[190:193], v[26:29]
	v_mfma_f32_16x16x32_bf16 v[18:21], v[130:133], v[204:207], v[18:21]
	v_mfma_f32_16x16x32_bf16 v[10:13], v[138:141], v[204:207], v[10:13]
	v_mfma_f32_16x16x32_bf16 v[62:65], v[134:137], v[178:181], v[62:65]
	v_mfma_f32_16x16x32_bf16 v[58:61], v[142:145], v[178:181], v[58:61]
	v_mfma_f32_16x16x32_bf16 v[50:53], v[134:137], v[186:189], v[50:53]
	v_mfma_f32_16x16x32_bf16 v[42:45], v[142:145], v[186:189], v[42:45]
	v_mfma_f32_16x16x32_bf16 v[34:37], v[134:137], v[200:203], v[34:37]
	v_mfma_f32_16x16x32_bf16 v[26:29], v[142:145], v[200:203], v[26:29]
	v_mfma_f32_16x16x32_bf16 v[18:21], v[134:137], v[208:211], v[18:21]
	v_mfma_f32_16x16x32_bf16 v[10:13], v[142:145], v[208:211], v[10:13]
	s_setprio 0
	s_setprio 1
	v_mfma_f32_16x16x32_bf16 v[54:57], v[146:149], v[162:165], v[54:57]
	v_mfma_f32_16x16x32_bf16 v[46:49], v[154:157], v[162:165], v[46:49]
	v_mfma_f32_16x16x32_bf16 v[38:41], v[146:149], v[182:185], v[38:41]
	v_mfma_f32_16x16x32_bf16 v[30:33], v[154:157], v[182:185], v[30:33]
	v_mfma_f32_16x16x32_bf16 v[22:25], v[146:149], v[190:193], v[22:25]
	v_mfma_f32_16x16x32_bf16 v[14:17], v[154:157], v[190:193], v[14:17]
	v_mfma_f32_16x16x32_bf16 v[6:9], v[146:149], v[204:207], v[6:9]
	v_mfma_f32_16x16x32_bf16 v[2:5], v[154:157], v[204:207], v[2:5]
	v_mfma_f32_16x16x32_bf16 v[54:57], v[150:153], v[178:181], v[54:57]
	v_mfma_f32_16x16x32_bf16 v[46:49], v[158:161], v[178:181], v[46:49]
	v_mfma_f32_16x16x32_bf16 v[38:41], v[150:153], v[186:189], v[38:41]
	v_mfma_f32_16x16x32_bf16 v[30:33], v[158:161], v[186:189], v[30:33]
	v_mfma_f32_16x16x32_bf16 v[22:25], v[150:153], v[200:203], v[22:25]
	v_mfma_f32_16x16x32_bf16 v[14:17], v[158:161], v[200:203], v[14:17]
	v_mfma_f32_16x16x32_bf16 v[6:9], v[150:153], v[208:211], v[6:9]
	v_mfma_f32_16x16x32_bf16 v[2:5], v[158:161], v[208:211], v[2:5]
	s_setprio 0
	s_barrier
	s_add_i32 s25, s25, 2
	s_add_u32 s54, s54, 0x100
	s_addc_u32 s55, s55, 0
	s_add_u32 s23, s23, 0x100
	s_addc_u32 s24, s24, 0
	s_cmp_gt_u32 s25, 13
	s_cbranch_scc0 .LBB0_165
	s_and_b64 vcc, exec, s[16:17]
	s_cbranch_vccz .LBB0_168
	s_barrier

; #define PG8_STAGE(bufoff, gbase, voff) do { _Pragma("unroll") for (int _i = 0; _i < 2; ++_i) \
;         __builtin_amdgcn_global_load_lds((const unsigned*)((const char*)(gbase) + (voff)[_i]), (PG8_LAS unsigned*)(lds + (bufoff) + ldsw + _i * 8192), 16, 0, 0); } while (0)
; #define PG8_LDA(dst, b, h) do { _Pragma("unroll") for (int m = 0; m < 4; ++m) _Pragma("unroll") for (int k = 0; k < 2; ++k) dst[m][k] = *(const PG8_LAS bf16x8*)(lds + PG8_SA(b, h) + aoff + m * 2048 + k * 1024); } while (0)
; #define PG8_LDB(dst, b, h) do { _Pragma("unroll") for (int n = 0; n < 2; ++n) _Pragma("unroll") for (int k = 0; k < 2; ++k) dst[n][k] = *(const PG8_LAS bf16x8*)(lds + PG8_SB(b, h) + boff + n * 2048 + k * 1024); } while (0)
; #define PG8_MMA(ai, bj, At, Bt) do { __builtin_amdgcn_s_setprio(1); _Pragma("unroll") for (int m = 0; m < 4; ++m) _Pragma("unroll") for (int n = 0; n < 2; ++n) _Pragma("unroll") for (int k = 0; k < 2; ++k) \
;         acc[ai][bj][m][n] = __builtin_amdgcn_mfma_f32_16x16x32_bf16(Bt[n][k], At[m][k], acc[ai][bj][m][n], 0, 0, 0); __builtin_amdgcn_s_setprio(0); } while (0)
; #define PG8_WAIT_V(n) asm volatile("s_waitcnt vmcnt(" #n ")" ::: "memory")
; #define PG8_WAIT_L(n) asm volatile("s_waitcnt lgkmcnt(" #n ")" ::: "memory")
; #define PG8_BAR __builtin_amdgcn_s_barrier()
; #define PG8_SCHED __builtin_amdgcn_sched_barrier(0)
; template <class Epi, class Sched, bool ALIGN_EPI = false, bool SP2 = false, bool SPLITK = false>
; __device__ __forceinline__ void gemm_phase(PG8_LAS unsigned char* lds, const Gemm g, const Sched& S, const Epi& E) {
;     ...
;             PG8_LDB(B0, 0, 0); PG8_LDB(B1, 0, 1); PG8_SCHED; PG8_LDA(At, 0, 0); PG8_STAGE(PG8_SA(1, 1), a1 + hstep, voffA);
;             PG8_WAIT_V(8); PG8_WAIT_L(0); PG8_BAR; PG8_MMA(0, 0, At, B0); PG8_MMA(0, 1, At, B1); PG8_BAR; PG8_SCHED;
;             PG8_LDA(At, 0, 1); PG8_STAGE(PG8_SB(0, 0), b2, voffB); PG8_STAGE(PG8_SB(0, 1), b2 + hstep, voffB); PG8_STAGE(PG8_SA(0, 0), a2, voffA);
;             PG8_WAIT_V(8); PG8_WAIT_L(0); PG8_BAR; PG8_MMA(1, 0, At, B0); PG8_MMA(1, 1, At, B1); PG8_BAR; PG8_SCHED;
.LBB0_582:
	s_add_u32 s46, s42, 0xfffc0080
	s_addc_u32 s47, s43, -1
	s_add_i32 s64, 0, 0x10000
	s_cmp_eq_u32 s45, 12
	s_cselect_b32 s49, s4, s47
	s_cselect_b32 s48, s12, s46
	s_cselect_b32 s47, s19, s41
	s_cselect_b32 s46, s21, s25
	s_add_i32 s68, 0, 0x14000
	v_add_u32_e32 v142, s64, v181
	v_add_u32_e32 v168, s68, v181
	ds_read_b128 v[130:133], v142
	ds_read_b128 v[134:137], v142 offset:1024
	ds_read_b128 v[138:141], v142 offset:2048
	ds_read_b128 v[142:145], v142 offset:3072
	ds_read_b128 v[156:159], v168
	ds_read_b128 v[160:163], v168 offset:1024
	ds_read_b128 v[164:167], v168 offset:2048
	ds_read_b128 v[170:173], v168 offset:3072
	s_add_i32 m0, s51, 0xc000
	ds_read_b128 v[176:179], v186
	ds_read_b128 v[182:185], v186 offset:1024
	ds_read_b128 v[188:191], v186 offset:2048
	ds_read_b128 v[192:195], v186 offset:3072
	ds_read_b128 v[196:199], v186 offset:4096
	ds_read_b128 v[200:203], v186 offset:5120
	ds_read_b128 v[204:207], v186 offset:6144
	ds_read_b128 v[208:211], v186 offset:7168
	global_load_lds_dwordx4 v152, s[42:43]
	s_add_i32 m0, s51, 0xe000
	s_nop 0
	global_load_lds_dwordx4 v154, s[42:43]
	s_waitcnt vmcnt(8)
	s_waitcnt lgkmcnt(0)
	s_barrier
	s_setprio 1
	s_waitcnt lgkmcnt(0)
	v_mfma_f32_16x16x32_bf16 v[126:129], v[130:133], v[176:179], v[126:129]
	v_mfma_f32_16x16x32_bf16 v[118:121], v[138:141], v[176:179], v[118:121]
	v_mfma_f32_16x16x32_bf16 v[110:113], v[130:133], v[188:191], v[110:113]
	v_mfma_f32_16x16x32_bf16 v[102:105], v[138:141], v[188:191], v[102:105]
	v_mfma_f32_16x16x32_bf16 v[94:97], v[130:133], v[196:199], v[94:97]
	v_mfma_f32_16x16x32_bf16 v[86:89], v[138:141], v[196:199], v[86:89]
	v_mfma_f32_16x16x32_bf16 v[78:81], v[130:133], v[204:207], v[78:81]
	v_mfma_f32_16x16x32_bf16 v[70:73], v[138:141], v[204:207], v[70:73]
	v_mfma_f32_16x16x32_bf16 v[126:129], v[134:137], v[182:185], v[126:129]
	v_mfma_f32_16x16x32_bf16 v[118:121], v[142:145], v[182:185], v[118:121]
	v_mfma_f32_16x16x32_bf16 v[110:113], v[134:137], v[192:195], v[110:113]
	v_mfma_f32_16x16x32_bf16 v[102:105], v[142:145], v[192:195], v[102:105]
	v_mfma_f32_16x16x32_bf16 v[94:97], v[134:137], v[200:203], v[94:97]
	v_mfma_f32_16x16x32_bf16 v[86:89], v[142:145], v[200:203], v[86:89]
	v_mfma_f32_16x16x32_bf16 v[78:81], v[134:137], v[208:211], v[78:81]
	v_mfma_f32_16x16x32_bf16 v[70:73], v[142:145], v[208:211], v[70:73]
	s_setprio 0
	s_setprio 1
	v_mfma_f32_16x16x32_bf16 v[122:125], v[156:159], v[176:179], v[122:125]
	v_mfma_f32_16x16x32_bf16 v[114:117], v[164:167], v[176:179], v[114:117]
	v_mfma_f32_16x16x32_bf16 v[106:109], v[156:159], v[188:191], v[106:109]
	v_mfma_f32_16x16x32_bf16 v[98:101], v[164:167], v[188:191], v[98:101]
	v_mfma_f32_16x16x32_bf16 v[90:93], v[156:159], v[196:199], v[90:93]
	v_mfma_f32_16x16x32_bf16 v[82:85], v[164:167], v[196:199], v[82:85]
	v_mfma_f32_16x16x32_bf16 v[74:77], v[156:159], v[204:207], v[74:77]
	v_mfma_f32_16x16x32_bf16 v[66:69], v[164:167], v[204:207], v[66:69]
	v_mfma_f32_16x16x32_bf16 v[122:125], v[160:163], v[182:185], v[122:125]
	v_mfma_f32_16x16x32_bf16 v[114:117], v[170:173], v[182:185], v[114:117]
	v_mfma_f32_16x16x32_bf16 v[106:109], v[160:163], v[192:195], v[106:109]
	v_mfma_f32_16x16x32_bf16 v[98:101], v[170:173], v[192:195], v[98:101]
	v_mfma_f32_16x16x32_bf16 v[90:93], v[160:163], v[200:203], v[90:93]
	v_mfma_f32_16x16x32_bf16 v[82:85], v[170:173], v[200:203], v[82:85]
	v_mfma_f32_16x16x32_bf16 v[74:77], v[160:163], v[208:211], v[74:77]
	v_mfma_f32_16x16x32_bf16 v[66:69], v[170:173], v[208:211], v[66:69]
	s_setprio 0
	s_barrier
	s_add_i32 s64, s64, s23
	s_mov_b32 m0, s64
	ds_read_b128 v[176:179], v186 offset:16384
	ds_read_b128 v[182:185], v186 offset:17408
	ds_read_b128 v[188:191], v186 offset:18432
	ds_read_b128 v[192:195], v186 offset:19456
	ds_read_b128 v[196:199], v186 offset:20480
	ds_read_b128 v[200:203], v186 offset:21504
	ds_read_b128 v[204:207], v186 offset:22528
	ds_read_b128 v[208:211], v186 offset:23552
	global_load_lds_dwordx4 v0, s[46:47]
	s_add_i32 m0, s64, 0x2000
	s_add_u32 s64, s46, 0x40000
	s_addc_u32 s65, s47, 0
	s_add_i32 s68, s68, s23
	global_load_lds_dwordx4 v146, s[46:47]
	s_mov_b32 m0, s68
	s_nop 0
	global_load_lds_dwordx4 v0, s[64:65]
	s_add_i32 m0, s68, 0x2000
	s_nop 0
	global_load_lds_dwordx4 v146, s[64:65]
	s_mov_b32 m0, s51
	s_nop 0
	global_load_lds_dwordx4 v150, s[48:49]
	s_mov_b32 m0, s52
	s_nop 0
	global_load_lds_dwordx4 v148, s[48:49]
	s_waitcnt vmcnt(8)
	s_waitcnt lgkmcnt(0)
	s_barrier
	s_setprio 1
	s_waitcnt lgkmcnt(0)
	v_mfma_f32_16x16x32_bf16 v[62:65], v[130:133], v[176:179], v[62:65]
	v_mfma_f32_16x16x32_bf16 v[54:57], v[138:141], v[176:179], v[54:57]
	v_mfma_f32_16x16x32_bf16 v[46:49], v[130:133], v[188:191], v[46:49]
	v_mfma_f32_16x16x32_bf16 v[38:41], v[138:141], v[188:191], v[38:41]
	v_mfma_f32_16x16x32_bf16 v[30:33], v[130:133], v[196:199], v[30:33]
	v_mfma_f32_16x16x32_bf16 v[22:25], v[138:141], v[196:199], v[22:25]
	v_mfma_f32_16x16x32_bf16 v[14:17], v[130:133], v[204:207], v[14:17]
	v_mfma_f32_16x16x32_bf16 v[6:9], v[138:141], v[204:207], v[6:9]
	v_mfma_f32_16x16x32_bf16 v[62:65], v[134:137], v[182:185], v[62:65]
	v_mfma_f32_16x16x32_bf16 v[54:57], v[142:145], v[182:185], v[54:57]
	v_mfma_f32_16x16x32_bf16 v[46:49], v[134:137], v[192:195], v[46:49]
	v_mfma_f32_16x16x32_bf16 v[38:41], v[142:145], v[192:195], v[38:41]
	v_mfma_f32_16x16x32_bf16 v[30:33], v[134:137], v[200:203], v[30:33]
	v_mfma_f32_16x16x32_bf16 v[22:25], v[142:145], v[200:203], v[22:25]
	v_mfma_f32_16x16x32_bf16 v[14:17], v[134:137], v[208:211], v[14:17]
	v_mfma_f32_16x16x32_bf16 v[6:9], v[142:145], v[208:211], v[6:9]
	s_setprio 0
	s_setprio 1
	v_mfma_f32_16x16x32_bf16 v[58:61], v[156:159], v[176:179], v[58:61]
	v_mfma_f32_16x16x32_bf16 v[50:53], v[164:167], v[176:179], v[50:53]
	v_mfma_f32_16x16x32_bf16 v[42:45], v[156:159], v[188:191], v[42:45]
	v_mfma_f32_16x16x32_bf16 v[34:37], v[164:167], v[188:191], v[34:37]
	v_mfma_f32_16x16x32_bf16 v[26:29], v[156:159], v[196:199], v[26:29]
	v_mfma_f32_16x16x32_bf16 v[18:21], v[164:167], v[196:199], v[18:21]
	v_mfma_f32_16x16x32_bf16 v[10:13], v[156:159], v[204:207], v[10:13]
	v_mfma_f32_16x16x32_bf16 v[2:5], v[164:167], v[204:207], v[2:5]
	v_mfma_f32_16x16x32_bf16 v[58:61], v[160:163], v[182:185], v[58:61]
	v_mfma_f32_16x16x32_bf16 v[50:53], v[170:173], v[182:185], v[50:53]
	v_mfma_f32_16x16x32_bf16 v[42:45], v[160:163], v[192:195], v[42:45]
	v_mfma_f32_16x16x32_bf16 v[34:37], v[170:173], v[192:195], v[34:37]
	v_mfma_f32_16x16x32_bf16 v[26:29], v[160:163], v[200:203], v[26:29]
	v_mfma_f32_16x16x32_bf16 v[18:21], v[170:173], v[200:203], v[18:21]
	v_mfma_f32_16x16x32_bf16 v[10:13], v[160:163], v[208:211], v[10:13]
	v_mfma_f32_16x16x32_bf16 v[2:5], v[170:173], v[208:211], v[2:5]
	s_setprio 0
	s_barrier
; #define PG8_STAGE(bufoff, gbase, voff) do { _Pragma("unroll") for (int _i = 0; _i < 2; ++_i) \
;         __builtin_amdgcn_global_load_lds((const unsigned*)((const char*)(gbase) + (voff)[_i]), (PG8_LAS unsigned*)(lds + (bufoff) + ldsw + _i * 8192), 16, 0, 0); } while (0)
; #define PG8_LDA(dst, b, h) do { _Pragma("unroll") for (int m = 0; m < 4; ++m) _Pragma("unroll") for (int k = 0; k < 2; ++k) dst[m][k] = *(const PG8_LAS bf16x8*)(lds + PG8_SA(b, h) + aoff + m * 2048 + k * 1024); } while (0)
; #define PG8_LDB(dst, b, h) do { _Pragma("unroll") for (int n = 0; n < 2; ++n) _Pragma("unroll") for (int k = 0; k < 2; ++k) dst[n][k] = *(const PG8_LAS bf16x8*)(lds + PG8_SB(b, h) + boff + n * 2048 + k * 1024); } while (0)
; #define PG8_MMA(ai, bj, At, Bt) do { __builtin_amdgcn_s_setprio(1); _Pragma("unroll") for (int m = 0; m < 4; ++m) _Pragma("unroll") for (int n = 0; n < 2; ++n) _Pragma("unroll") for (int k = 0; k < 2; ++k) \
;         acc[ai][bj][m][n] = __builtin_amdgcn_mfma_f32_16x16x32_bf16(Bt[n][k], At[m][k], acc[ai][bj][m][n], 0, 0, 0); __builtin_amdgcn_s_setprio(0); } while (0)
; #define PG8_WAIT_V(n) asm volatile("s_waitcnt vmcnt(" #n ")" ::: "memory")
; #define PG8_WAIT_L(n) asm volatile("s_waitcnt lgkmcnt(" #n ")" ::: "memory")
; template <class Epi, class Sched, bool ALIGN_EPI = false, bool SP2 = false, bool SPLITK = false>
; __device__ __forceinline__ void gemm_phase(PG8_LAS unsigned char* lds, const Gemm g, const Sched& S, const Epi& E) {
;     ...
;         for (int t = 0; t < nt; t += 2) {
;             const bool last = (t == nt - 2);
;             if constexpr (SPLITK) { if (t == nt1) E.mid(acc, cur, wr, wc, fr, fq); }
;             const char* a1 = PG8_TA(t + 1);
;             const char* a2 = last ? nA : PG8_TA(t + 2); const char* b2 = last ? nB : PG8_TB(t + 2);
;             const char* a3 = a2 + kstep; const char* b3 = b2 + kstep;
;     ...
;             PG8_LDB(B0, 1, 0); PG8_LDB(B1, 1, 1); PG8_SCHED; PG8_LDA(At, 1, 0); PG8_STAGE(PG8_SA(0, 1), a2 + hstep, voffA);
;             PG8_WAIT_V(8); PG8_WAIT_L(0); PG8_BAR; PG8_MMA(0, 0, At, B0); PG8_MMA(0, 1, At, B1); PG8_BAR; PG8_SCHED;
;             PG8_LDA(At, 1, 1); PG8_STAGE(PG8_SB(1, 0), b3, voffB); PG8_STAGE(PG8_SB(1, 1), b3 + hstep, voffB); PG8_STAGE(PG8_SA(1, 0), a3, voffA);
;             PG8_WAIT_V(8); PG8_WAIT_L(0); PG8_BAR; PG8_MMA(1, 0, At, B0); PG8_MMA(1, 1, At, B1); PG8_BAR; PG8_SCHED;
	s_add_i32 s64, 0, 0x18000
	s_add_i32 s65, 0, 0x1c000
	v_add_u32_e32 v142, s64, v181
	v_add_u32_e32 v168, s65, v181
	ds_read_b128 v[130:133], v142
	ds_read_b128 v[134:137], v142 offset:1024
	ds_read_b128 v[138:141], v142 offset:2048
	ds_read_b128 v[142:145], v142 offset:3072
	ds_read_b128 v[156:159], v168
	ds_read_b128 v[160:163], v168 offset:1024
	ds_read_b128 v[164:167], v168 offset:2048
	ds_read_b128 v[170:173], v168 offset:3072
	s_add_u32 vcc_lo, s48, 0x80
	s_addc_u32 vcc_hi, s49, 0
	s_add_u32 s48, s48, 0x40000
	s_addc_u32 s49, s49, 0
	s_mov_b32 m0, s53
	ds_read_b128 v[176:179], v186 offset:32768
	ds_read_b128 v[182:185], v186 offset:33792
	ds_read_b128 v[188:191], v186 offset:34816
	ds_read_b128 v[192:195], v186 offset:35840
	ds_read_b128 v[196:199], v186 offset:36864
	ds_read_b128 v[200:203], v186 offset:37888
	ds_read_b128 v[204:207], v186 offset:38912
	ds_read_b128 v[208:211], v186 offset:39936
	global_load_lds_dwordx4 v150, s[48:49]
	s_mov_b32 m0, s54
	s_nop 0
	global_load_lds_dwordx4 v148, s[48:49]
	s_waitcnt vmcnt(8)
	s_waitcnt lgkmcnt(0)
	s_barrier
	s_setprio 1
	s_waitcnt lgkmcnt(0)
	v_mfma_f32_16x16x32_bf16 v[126:129], v[130:133], v[176:179], v[126:129]
	v_mfma_f32_16x16x32_bf16 v[118:121], v[138:141], v[176:179], v[118:121]
	v_mfma_f32_16x16x32_bf16 v[110:113], v[130:133], v[188:191], v[110:113]
	v_mfma_f32_16x16x32_bf16 v[102:105], v[138:141], v[188:191], v[102:105]
	v_mfma_f32_16x16x32_bf16 v[94:97], v[130:133], v[196:199], v[94:97]
	v_mfma_f32_16x16x32_bf16 v[86:89], v[138:141], v[196:199], v[86:89]
	v_mfma_f32_16x16x32_bf16 v[78:81], v[130:133], v[204:207], v[78:81]
	v_mfma_f32_16x16x32_bf16 v[70:73], v[138:141], v[204:207], v[70:73]
	v_mfma_f32_16x16x32_bf16 v[126:129], v[134:137], v[182:185], v[126:129]
	v_mfma_f32_16x16x32_bf16 v[118:121], v[142:145], v[182:185], v[118:121]
	v_mfma_f32_16x16x32_bf16 v[110:113], v[134:137], v[192:195], v[110:113]
	v_mfma_f32_16x16x32_bf16 v[102:105], v[142:145], v[192:195], v[102:105]
	v_mfma_f32_16x16x32_bf16 v[94:97], v[134:137], v[200:203], v[94:97]
	v_mfma_f32_16x16x32_bf16 v[86:89], v[142:145], v[200:203], v[86:89]
	v_mfma_f32_16x16x32_bf16 v[78:81], v[134:137], v[208:211], v[78:81]
	v_mfma_f32_16x16x32_bf16 v[70:73], v[142:145], v[208:211], v[70:73]
	s_setprio 0
	s_setprio 1
	v_mfma_f32_16x16x32_bf16 v[122:125], v[156:159], v[176:179], v[122:125]
	v_mfma_f32_16x16x32_bf16 v[114:117], v[164:167], v[176:179], v[114:117]
	v_mfma_f32_16x16x32_bf16 v[106:109], v[156:159], v[188:191], v[106:109]
	v_mfma_f32_16x16x32_bf16 v[98:101], v[164:167], v[188:191], v[98:101]
	v_mfma_f32_16x16x32_bf16 v[90:93], v[156:159], v[196:199], v[90:93]
	v_mfma_f32_16x16x32_bf16 v[82:85], v[164:167], v[196:199], v[82:85]
	v_mfma_f32_16x16x32_bf16 v[74:77], v[156:159], v[204:207], v[74:77]
	v_mfma_f32_16x16x32_bf16 v[66:69], v[164:167], v[204:207], v[66:69]
	v_mfma_f32_16x16x32_bf16 v[122:125], v[160:163], v[182:185], v[122:125]
	v_mfma_f32_16x16x32_bf16 v[114:117], v[170:173], v[182:185], v[114:117]
	v_mfma_f32_16x16x32_bf16 v[106:109], v[160:163], v[192:195], v[106:109]
	v_mfma_f32_16x16x32_bf16 v[98:101], v[170:173], v[192:195], v[98:101]
	v_mfma_f32_16x16x32_bf16 v[90:93], v[160:163], v[200:203], v[90:93]
	v_mfma_f32_16x16x32_bf16 v[82:85], v[170:173], v[200:203], v[82:85]
	v_mfma_f32_16x16x32_bf16 v[74:77], v[160:163], v[208:211], v[74:77]
	v_mfma_f32_16x16x32_bf16 v[66:69], v[170:173], v[208:211], v[66:69]
	s_setprio 0
	s_barrier
	s_add_i32 s48, s64, s23
	s_add_u32 s46, s46, 0x80
	s_addc_u32 s47, s47, 0
	s_mov_b32 m0, s48
	ds_read_b128 v[176:179], v186 offset:49152
	ds_read_b128 v[182:185], v186 offset:50176
	ds_read_b128 v[188:191], v186 offset:51200
	ds_read_b128 v[192:195], v186 offset:52224
	ds_read_b128 v[196:199], v186 offset:53248
	ds_read_b128 v[200:203], v186 offset:54272
	ds_read_b128 v[204:207], v186 offset:55296
	ds_read_b128 v[208:211], v186 offset:56320
	global_load_lds_dwordx4 v0, s[46:47]
	s_add_i32 m0, s48, 0x2000
	s_add_i32 s48, s65, s23
	global_load_lds_dwordx4 v146, s[46:47]
	s_add_u32 s46, s46, 0x40000
	s_addc_u32 s47, s47, 0
	s_mov_b32 m0, s48
	s_nop 0
	global_load_lds_dwordx4 v0, s[46:47]
	s_add_i32 m0, s48, 0x2000
	s_nop 0
	global_load_lds_dwordx4 v146, s[46:47]
	s_mov_b32 m0, s55
	s_nop 0
	global_load_lds_dwordx4 v150, vcc
	s_mov_b32 m0, s56
	s_nop 0
	global_load_lds_dwordx4 v148, vcc
	s_waitcnt vmcnt(8)
	s_waitcnt lgkmcnt(0)
	s_barrier
	s_setprio 1
	s_waitcnt lgkmcnt(0)
	v_mfma_f32_16x16x32_bf16 v[62:65], v[130:133], v[176:179], v[62:65]
	v_mfma_f32_16x16x32_bf16 v[54:57], v[138:141], v[176:179], v[54:57]
	v_mfma_f32_16x16x32_bf16 v[46:49], v[130:133], v[188:191], v[46:49]
	v_mfma_f32_16x16x32_bf16 v[38:41], v[138:141], v[188:191], v[38:41]
	v_mfma_f32_16x16x32_bf16 v[30:33], v[130:133], v[196:199], v[30:33]
	v_mfma_f32_16x16x32_bf16 v[22:25], v[138:141], v[196:199], v[22:25]
	v_mfma_f32_16x16x32_bf16 v[14:17], v[130:133], v[204:207], v[14:17]
	v_mfma_f32_16x16x32_bf16 v[6:9], v[138:141], v[204:207], v[6:9]
	v_mfma_f32_16x16x32_bf16 v[62:65], v[134:137], v[182:185], v[62:65]
	v_mfma_f32_16x16x32_bf16 v[54:57], v[142:145], v[182:185], v[54:57]
	v_mfma_f32_16x16x32_bf16 v[46:49], v[134:137], v[192:195], v[46:49]
	v_mfma_f32_16x16x32_bf16 v[38:41], v[142:145], v[192:195], v[38:41]
	v_mfma_f32_16x16x32_bf16 v[30:33], v[134:137], v[200:203], v[30:33]
	v_mfma_f32_16x16x32_bf16 v[22:25], v[142:145], v[200:203], v[22:25]
	v_mfma_f32_16x16x32_bf16 v[14:17], v[134:137], v[208:211], v[14:17]
	v_mfma_f32_16x16x32_bf16 v[6:9], v[142:145], v[208:211], v[6:9]
	s_setprio 0
	s_setprio 1
	v_mfma_f32_16x16x32_bf16 v[58:61], v[156:159], v[176:179], v[58:61]
	v_mfma_f32_16x16x32_bf16 v[50:53], v[164:167], v[176:179], v[50:53]
	v_mfma_f32_16x16x32_bf16 v[42:45], v[156:159], v[188:191], v[42:45]
	v_mfma_f32_16x16x32_bf16 v[34:37], v[164:167], v[188:191], v[34:37]
	v_mfma_f32_16x16x32_bf16 v[26:29], v[156:159], v[196:199], v[26:29]
	v_mfma_f32_16x16x32_bf16 v[18:21], v[164:167], v[196:199], v[18:21]
	v_mfma_f32_16x16x32_bf16 v[10:13], v[156:159], v[204:207], v[10:13]
	v_mfma_f32_16x16x32_bf16 v[2:5], v[164:167], v[204:207], v[2:5]
	v_mfma_f32_16x16x32_bf16 v[58:61], v[160:163], v[182:185], v[58:61]
	v_mfma_f32_16x16x32_bf16 v[50:53], v[170:173], v[182:185], v[50:53]
	v_mfma_f32_16x16x32_bf16 v[42:45], v[160:163], v[192:195], v[42:45]
	v_mfma_f32_16x16x32_bf16 v[34:37], v[170:173], v[192:195], v[34:37]
	v_mfma_f32_16x16x32_bf16 v[26:29], v[160:163], v[200:203], v[26:29]
	v_mfma_f32_16x16x32_bf16 v[18:21], v[170:173], v[200:203], v[18:21]
	v_mfma_f32_16x16x32_bf16 v[10:13], v[160:163], v[208:211], v[10:13]
	v_mfma_f32_16x16x32_bf16 v[2:5], v[170:173], v[208:211], v[2:5]
	s_setprio 0
	s_barrier
	s_add_i32 s45, s45, 2
	s_add_u32 s42, s42, 0x100
	s_addc_u32 s43, s43, 0
	s_add_u32 s25, s25, 0x100
	s_addc_u32 s41, s41, 0
	s_cmp_gt_u32 s45, 13
	s_cbranch_scc0 .LBB0_582
	s_and_b64 vcc, exec, s[16:17]
	s_cbranch_vccz .LBB0_585
	s_barrier
